# MFMA-DMA interleave: B (MLA) loop K/V LDS-DMA issue moved from MFMA gap 5 to gap 9 on top of v47
# speedup vs baseline: 1.0103x; 1.0101x over previous
; #define SBAR() __builtin_amdgcn_sched_barrier(0)
; #define SGB(mask, n) __builtin_amdgcn_sched_group_barrier(mask, n, 0)
; #define BLOAD(b, k0) do { _Pragma("unroll") for (int i = 0; i < 3; ++i) glds16(Kh + (long)(k0) * 768 + bkoff[i], K_lds + (b) * 24576 + ldst[i]); \
;     _Pragma("unroll") for (int i = 0; i < 2; ++i) glds16(Vh + (long)(k0) * 512 + bvoff[i], V_lds + (b) * 16384 + ldst[i]); } while (0)
; DEV void attn_b_item(const Params& P, int layer, int batch, int item, char* lds) {
;     ...
;     {
;       bf16x8 kf[12];
; #pragma unroll
;       for (int ks = 0; ks < 12; ++ks) kf[ks] = *reinterpret_cast<const bf16x8*>(Ks + kq + (((ks * 2 + hi) ^ ksw) << 4));
; #pragma unroll
;       for (int ks = 0; ks < 12; ++ks) p0 = __builtin_amdgcn_mfma_f32_32x32x16_bf16(kf[ks], qr[ks], p0, 0, 0, 0);
;       SGB(0x100, 4); SGB(0x008, 2); SGB(0x100, 2); SGB(0x008, 2); SGB(0x100, 2); SGB(0x008, 2); SGB(0x100, 2); SGB(0x008, 2); SGB(0x100, 2); SGB(0x008, 4);
;     }
;     SBAR();
;     if (j + 1 < NT) BLOAD((j + 1) & 1, (j + 1) * 64);
;     SBAR();
;     {
;       trq<0, 0>(vb, fa);
;       bf16x8 kf[12];
; #pragma unroll
;       for (int ks = 0; ks < 12; ++ks) kf[ks] = *reinterpret_cast<const bf16x8*>(Ks + kq + 32 * 384 + (((ks * 2 + hi) ^ ksw) << 4));
; #pragma unroll
;       for (int ks = 0; ks < 12; ++ks) p1 = __builtin_amdgcn_mfma_f32_32x32x16_bf16(kf[ks], qr[ks], p1, 0, 0, 0);
;       sm_exp(p0, lsum); sm_pack(p0, pa0, pa1);
;     }
;     asm volatile("s_waitcnt lgkmcnt(0)" ::: "memory"); SBAR();
;     trq<0, 2>(vb, fb);
;     mmaq(o[0], o[1], fa, pa0, pa1);
;     sm_exp(p1, lsum);
;     asm volatile("s_waitcnt lgkmcnt(0)" ::: "memory"); SBAR();
;     trq<2, 0>(vb, fa);
;     mmaq(o[2], o[3], fb, pa0, pa1);
.Lmla_loop:
	ds_read_b128 v[218:221], v169 offset:0
	ds_read_b128 v[232:235], v170 offset:0
	ds_read_b128 v[236:239], v171 offset:0
	ds_read_b128 v[240:243], v172 offset:0
	ds_read_b128 v[244:247], v169 offset:128
	ds_read_b128 v[248:251], v170 offset:128
	v_mfma_f32_32x32x16_bf16 v[48:63], v[198:201], v[202:205], v[48:63]
	ds_read_b128 v[202:205], v171 offset:128
	v_mfma_f32_32x32x16_bf16 v[32:47], v[198:201], v[206:209], v[32:47]
	ds_read_b128 v[206:209], v172 offset:128
	v_mfma_f32_32x32x16_bf16 v[16:31], v[198:201], v[210:213], v[16:31]
	ds_read_b128 v[210:213], v169 offset:256
	v_mfma_f32_32x32x16_bf16 v[0:15], v[198:201], v[214:217], v[0:15]
	ds_read_b128 v[214:217], v170 offset:256
	s_waitcnt lgkmcnt(9)
	v_mfma_f32_32x32x16_bf16 v[64:79], v[218:221], v[96:99], 0
	ds_read_b128 v[218:221], v171 offset:256
	v_add_f32_e32 v182, v182, v80
	v_add_f32_e32 v182, v182, v81
	s_waitcnt lgkmcnt(9)
	v_mfma_f32_32x32x16_bf16 v[64:79], v[232:235], v[100:103], v[64:79]
	ds_read_b128 v[232:235], v172 offset:256
	v_add_f32_e32 v182, v182, v82
	s_waitcnt lgkmcnt(9)
	v_mfma_f32_32x32x16_bf16 v[64:79], v[236:239], v[104:107], v[64:79]
	ds_read_b128 v[236:239], v169 offset:12288
	v_add_f32_e32 v182, v182, v83
	s_waitcnt lgkmcnt(9)
	v_mfma_f32_32x32x16_bf16 v[64:79], v[240:243], v[108:111], v[64:79]
	ds_read_b128 v[240:243], v170 offset:12288
	v_add_f32_e32 v182, v182, v84
	v_add_f32_e32 v182, v182, v85
	s_waitcnt lgkmcnt(9)
	v_mfma_f32_32x32x16_bf16 v[64:79], v[244:247], v[112:115], v[64:79]
	ds_read_b128 v[244:247], v171 offset:12288
	v_add_f32_e32 v182, v182, v86
	s_waitcnt lgkmcnt(9)
	v_mfma_f32_32x32x16_bf16 v[64:79], v[248:251], v[116:119], v[64:79]
	ds_read_b128 v[248:251], v172 offset:12288
	v_add_f32_e32 v182, v182, v87
	s_add_u32 m0, s100, 0x6000
	s_nop 0
	global_load_lds_dwordx4 v146, s[68:69]
	s_add_u32 m0, s101, 0x4000
	s_nop 0
	global_load_lds_dwordx4 v148, s[70:71]
	s_add_u32 m0, s100, 0x8000
	s_nop 0
	global_load_lds_dwordx4 v150, s[68:69]
	s_add_u32 m0, s101, 0x6000
	s_nop 0
	global_load_lds_dwordx4 v152, s[70:71]
	s_add_u32 m0, s100, 0xa000
	s_nop 0
	global_load_lds_dwordx4 v154, s[68:69]
	s_add_u32 s68, s68, 0x18000
	s_addc_u32 s69, s69, 0
	s_add_u32 s70, s70, 0x10000
	s_addc_u32 s71, s71, 0
	s_waitcnt lgkmcnt(9)
	v_mfma_f32_32x32x16_bf16 v[64:79], v[202:205], v[120:123], v[64:79]
	ds_read_b128 v[202:205], v169 offset:12416
	v_add_f32_e32 v182, v182, v88
	v_add_f32_e32 v182, v182, v89
	s_waitcnt lgkmcnt(9)
	v_mfma_f32_32x32x16_bf16 v[64:79], v[206:209], v[124:127], v[64:79]
	ds_read_b128 v[206:209], v170 offset:12416
	v_add_f32_e32 v182, v182, v90
	s_waitcnt lgkmcnt(9)
	v_mfma_f32_32x32x16_bf16 v[64:79], v[210:213], v[128:131], v[64:79]
	ds_read_b128 v[210:213], v171 offset:12416
	v_add_f32_e32 v182, v182, v91
	s_waitcnt lgkmcnt(9)
	v_mfma_f32_32x32x16_bf16 v[64:79], v[214:217], v[132:135], v[64:79]
	ds_read_b128 v[214:217], v172 offset:12416
	v_add_f32_e32 v182, v182, v92
	v_add_f32_e32 v182, v182, v93
	s_waitcnt lgkmcnt(9)
	v_mfma_f32_32x32x16_bf16 v[64:79], v[218:221], v[136:139], v[64:79]
	ds_read_b128 v[218:221], v169 offset:12544
	v_add_f32_e32 v182, v182, v94
	s_waitcnt lgkmcnt(9)
	v_mfma_f32_32x32x16_bf16 v[64:79], v[232:235], v[140:143], v[64:79]
	ds_read_b128 v[232:235], v170 offset:12544
	v_add_f32_e32 v182, v182, v95
	s_waitcnt lgkmcnt(9)
	v_mfma_f32_32x32x16_bf16 v[80:95], v[236:239], v[96:99], 0
	ds_read_b128 v[236:239], v171 offset:12544
	s_waitcnt lgkmcnt(9)
	v_mfma_f32_32x32x16_bf16 v[80:95], v[240:243], v[100:103], v[80:95]
	ds_read_b128 v[240:243], v172 offset:12544
	s_waitcnt lgkmcnt(9)
	v_mfma_f32_32x32x16_bf16 v[80:95], v[244:247], v[104:107], v[80:95]
	ds_read_b64_tr_b16 v[244:245], v166 offset:0
	ds_read_b64_tr_b16 v[246:247], v166 offset:2048
	s_waitcnt lgkmcnt(10)
	v_mfma_f32_32x32x16_bf16 v[80:95], v[248:251], v[108:111], v[80:95]
	ds_read_b64_tr_b16 v[248:249], v166 offset:512
	ds_read_b64_tr_b16 v[250:251], v166 offset:2560
	v_exp_f32_e32 v64, v64
	v_exp_f32_e32 v65, v65
	s_waitcnt lgkmcnt(11)
	v_mfma_f32_32x32x16_bf16 v[80:95], v[202:205], v[112:115], v[80:95]
	ds_read_b64_tr_b16 v[202:203], v166 offset:1024
	ds_read_b64_tr_b16 v[204:205], v166 offset:3072
	v_exp_f32_e32 v66, v66
	v_exp_f32_e32 v67, v67
	s_waitcnt lgkmcnt(12)
	v_mfma_f32_32x32x16_bf16 v[80:95], v[206:209], v[116:119], v[80:95]
	ds_read_b64_tr_b16 v[206:207], v166 offset:1536
	ds_read_b64_tr_b16 v[208:209], v166 offset:3584
	v_exp_f32_e32 v68, v68
	v_exp_f32_e32 v69, v69
	s_waitcnt lgkmcnt(13)
	v_mfma_f32_32x32x16_bf16 v[80:95], v[210:213], v[120:123], v[80:95]
	ds_read_b64_tr_b16 v[210:211], v166 offset:4096
	ds_read_b64_tr_b16 v[212:213], v166 offset:6144
	v_exp_f32_e32 v70, v70
	v_exp_f32_e32 v71, v71
	s_waitcnt lgkmcnt(14)
	v_mfma_f32_32x32x16_bf16 v[80:95], v[214:217], v[124:127], v[80:95]
	ds_read_b64_tr_b16 v[214:215], v166 offset:4608
	ds_read_b64_tr_b16 v[216:217], v166 offset:6656
	v_cvt_pk_bf16_f32 v174, v64, v65
	v_exp_f32_e32 v72, v72
	v_exp_f32_e32 v73, v73
	s_waitcnt lgkmcnt(14)
	v_mfma_f32_32x32x16_bf16 v[80:95], v[218:221], v[128:131], v[80:95]
	ds_read_b64_tr_b16 v[218:219], v166 offset:5120
	ds_read_b64_tr_b16 v[220:221], v166 offset:7168
	v_cvt_pk_bf16_f32 v175, v66, v67
	v_exp_f32_e32 v74, v74
	v_exp_f32_e32 v75, v75
	s_waitcnt lgkmcnt(14)
	v_mfma_f32_32x32x16_bf16 v[80:95], v[232:235], v[132:135], v[80:95]
	ds_read_b64_tr_b16 v[232:233], v166 offset:5632
	ds_read_b64_tr_b16 v[234:235], v166 offset:7680
	v_cvt_pk_bf16_f32 v176, v68, v69
	v_exp_f32_e32 v76, v76
	v_exp_f32_e32 v77, v77
	s_waitcnt lgkmcnt(14)
; #define SBAR() __builtin_amdgcn_sched_barrier(0)
; #define SGB(mask, n) __builtin_amdgcn_sched_group_barrier(mask, n, 0)
; #define BLOAD(b, k0) do { _Pragma("unroll") for (int i = 0; i < 3; ++i) glds16(Kh + (long)(k0) * 768 + bkoff[i], K_lds + (b) * 24576 + ldst[i]); \
;     _Pragma("unroll") for (int i = 0; i < 2; ++i) glds16(Vh + (long)(k0) * 512 + bvoff[i], V_lds + (b) * 16384 + ldst[i]); } while (0)
; DEV void attn_b_item(const Params& P, int layer, int batch, int item, char* lds) {
;     ...
;     {
;       bf16x8 kf[12];
; #pragma unroll
;       for (int ks = 0; ks < 12; ++ks) kf[ks] = *reinterpret_cast<const bf16x8*>(Ks + kq + (((ks * 2 + hi) ^ ksw) << 4));
; #pragma unroll
;       for (int ks = 0; ks < 12; ++ks) p0 = __builtin_amdgcn_mfma_f32_32x32x16_bf16(kf[ks], qr[ks], p0, 0, 0, 0);
;       SGB(0x100, 4); SGB(0x008, 2); SGB(0x100, 2); SGB(0x008, 2); SGB(0x100, 2); SGB(0x008, 2); SGB(0x100, 2); SGB(0x008, 2); SGB(0x100, 2); SGB(0x008, 4);
;     }
;     SBAR();
;     if (j + 1 < NT) BLOAD((j + 1) & 1, (j + 1) * 64);
;     SBAR();
;     {
;       trq<0, 0>(vb, fa);
;       bf16x8 kf[12];
; #pragma unroll
;       for (int ks = 0; ks < 12; ++ks) kf[ks] = *reinterpret_cast<const bf16x8*>(Ks + kq + 32 * 384 + (((ks * 2 + hi) ^ ksw) << 4));
; #pragma unroll
;       for (int ks = 0; ks < 12; ++ks) p1 = __builtin_amdgcn_mfma_f32_32x32x16_bf16(kf[ks], qr[ks], p1, 0, 0, 0);
;       sm_exp(p0, lsum); sm_pack(p0, pa0, pa1);
;     }
;     asm volatile("s_waitcnt lgkmcnt(0)" ::: "memory"); SBAR();
;     trq<0, 2>(vb, fb);
;     mmaq(o[0], o[1], fa, pa0, pa1);
;     sm_exp(p1, lsum);
;     asm volatile("s_waitcnt lgkmcnt(0)" ::: "memory"); SBAR();
;     trq<2, 0>(vb, fa);
;     mmaq(o[2], o[3], fb, pa0, pa1);
;     sm_pack(p1, pa2, pa3);
;     asm volatile("s_waitcnt lgkmcnt(0)" ::: "memory"); SBAR();
;     trq<2, 2>(vb, fb);
;     mmaq(o[0], o[1], fa, pa2, pa3);
;     asm volatile("s_waitcnt lgkmcnt(0)" ::: "memory"); SBAR();
;     mmaq(o[2], o[3], fb, pa2, pa3);
;     asm volatile("s_waitcnt vmcnt(0)" ::: "memory");
;     __syncthreads();
	v_mfma_f32_32x32x16_bf16 v[80:95], v[236:239], v[136:139], v[80:95]
	ds_read_b64_tr_b16 v[236:237], v166 offset:8192
	ds_read_b64_tr_b16 v[238:239], v166 offset:10240
	v_cvt_pk_bf16_f32 v177, v70, v71
	v_exp_f32_e32 v78, v78
	v_exp_f32_e32 v79, v79
	s_waitcnt lgkmcnt(14)
	v_mfma_f32_32x32x16_bf16 v[80:95], v[240:243], v[140:143], v[80:95]
	ds_read_b64_tr_b16 v[240:241], v166 offset:8704
	ds_read_b64_tr_b16 v[242:243], v166 offset:10752
	v_cvt_pk_bf16_f32 v178, v72, v73
	v_cvt_pk_bf16_f32 v179, v74, v75
	v_cvt_pk_bf16_f32 v180, v76, v77
	v_cvt_pk_bf16_f32 v181, v78, v79
	s_waitcnt lgkmcnt(14)
	v_mfma_f32_32x32x16_bf16 v[48:63], v[174:177], v[244:247], v[48:63]
	ds_read_b64_tr_b16 v[244:245], v166 offset:9216
	ds_read_b64_tr_b16 v[246:247], v166 offset:11264
	v_add_f32_e32 v182, v182, v64
	v_add_f32_e32 v182, v182, v65
	v_add_f32_e32 v182, v182, v66
	v_add_f32_e32 v182, v182, v67
	s_waitcnt lgkmcnt(14)
	v_mfma_f32_32x32x16_bf16 v[32:47], v[174:177], v[248:251], v[32:47]
	ds_read_b64_tr_b16 v[248:249], v166 offset:9728
	ds_read_b64_tr_b16 v[250:251], v166 offset:11776
	v_add_f32_e32 v182, v182, v68
	v_add_f32_e32 v182, v182, v69
	v_add_f32_e32 v182, v182, v70
	v_add_f32_e32 v182, v182, v71
	s_waitcnt lgkmcnt(14)
	v_mfma_f32_32x32x16_bf16 v[16:31], v[174:177], v[202:205], v[16:31]
	ds_read_b64_tr_b16 v[202:203], v166 offset:12288
	ds_read_b64_tr_b16 v[204:205], v166 offset:14336
	v_add_f32_e32 v182, v182, v72
	v_add_f32_e32 v182, v182, v73
	v_add_f32_e32 v182, v182, v74
	v_add_f32_e32 v182, v182, v75
	s_waitcnt lgkmcnt(14)
	v_mfma_f32_32x32x16_bf16 v[0:15], v[174:177], v[206:209], v[0:15]
	ds_read_b64_tr_b16 v[206:207], v166 offset:12800
	ds_read_b64_tr_b16 v[208:209], v166 offset:14848
	v_exp_f32_e32 v80, v80
	v_exp_f32_e32 v81, v81
	v_exp_f32_e32 v82, v82
	s_waitcnt lgkmcnt(14)
	v_mfma_f32_32x32x16_bf16 v[48:63], v[178:181], v[210:213], v[48:63]
	ds_read_b64_tr_b16 v[210:211], v166 offset:13312
	ds_read_b64_tr_b16 v[212:213], v166 offset:15360
	v_exp_f32_e32 v83, v83
	v_exp_f32_e32 v84, v84
	v_exp_f32_e32 v85, v85
	s_waitcnt lgkmcnt(14)
	v_mfma_f32_32x32x16_bf16 v[32:47], v[178:181], v[214:217], v[32:47]
	ds_read_b64_tr_b16 v[214:215], v166 offset:13824
	ds_read_b64_tr_b16 v[216:217], v166 offset:15872
	v_exp_f32_e32 v86, v86
	v_exp_f32_e32 v87, v87
	v_exp_f32_e32 v88, v88
	s_waitcnt lgkmcnt(14)
	v_mfma_f32_32x32x16_bf16 v[16:31], v[178:181], v[218:221], v[16:31]
	v_cvt_pk_bf16_f32 v194, v80, v81
	v_cvt_pk_bf16_f32 v195, v82, v83
	v_exp_f32_e32 v89, v89
	v_exp_f32_e32 v90, v90
	v_exp_f32_e32 v91, v91
	s_waitcnt lgkmcnt(14)
	v_mfma_f32_32x32x16_bf16 v[0:15], v[178:181], v[232:235], v[0:15]
	v_cvt_pk_bf16_f32 v196, v84, v85
	v_cvt_pk_bf16_f32 v197, v86, v87
	v_exp_f32_e32 v92, v92
	v_exp_f32_e32 v93, v93
	s_waitcnt lgkmcnt(14)
	v_mfma_f32_32x32x16_bf16 v[48:63], v[194:197], v[236:239], v[48:63]
	v_exp_f32_e32 v94, v94
	v_exp_f32_e32 v95, v95
	s_waitcnt lgkmcnt(12)
	v_mfma_f32_32x32x16_bf16 v[32:47], v[194:197], v[240:243], v[32:47]
	v_cvt_pk_bf16_f32 v198, v88, v89
	v_cvt_pk_bf16_f32 v199, v90, v91
	v_add_f32_e32 v182, v182, v76
	v_add_f32_e32 v182, v182, v77
	s_waitcnt lgkmcnt(10)
	v_mfma_f32_32x32x16_bf16 v[16:31], v[194:197], v[244:247], v[16:31]
	v_cvt_pk_bf16_f32 v200, v92, v93
	v_cvt_pk_bf16_f32 v201, v94, v95
	v_add_f32_e32 v182, v182, v78
	v_add_f32_e32 v182, v182, v79
	s_waitcnt lgkmcnt(8)
	v_mfma_f32_32x32x16_bf16 v[0:15], v[194:197], v[248:251], v[0:15]
	s_waitcnt lgkmcnt(0)
	s_waitcnt vmcnt(0)
	s_barrier
	ds_read_b128 v[218:221], v169 offset:24576
	ds_read_b128 v[232:235], v170 offset:24576
	ds_read_b128 v[236:239], v171 offset:24576
	ds_read_b128 v[240:243], v172 offset:24576
	ds_read_b128 v[244:247], v169 offset:24704
	ds_read_b128 v[248:251], v170 offset:24704
	v_mfma_f32_32x32x16_bf16 v[48:63], v[198:201], v[202:205], v[48:63]
	ds_read_b128 v[202:205], v171 offset:24704
	v_mfma_f32_32x32x16_bf16 v[32:47], v[198:201], v[206:209], v[32:47]
	ds_read_b128 v[206:209], v172 offset:24704
	v_mfma_f32_32x32x16_bf16 v[16:31], v[198:201], v[210:213], v[16:31]
	ds_read_b128 v[210:213], v169 offset:24832
	v_mfma_f32_32x32x16_bf16 v[0:15], v[198:201], v[214:217], v[0:15]
	ds_read_b128 v[214:217], v170 offset:24832
	s_waitcnt lgkmcnt(9)
	v_mfma_f32_32x32x16_bf16 v[64:79], v[218:221], v[96:99], 0
	ds_read_b128 v[218:221], v171 offset:24832
	v_add_f32_e32 v182, v182, v80
	v_add_f32_e32 v182, v182, v81
	s_waitcnt lgkmcnt(9)
	v_mfma_f32_32x32x16_bf16 v[64:79], v[232:235], v[100:103], v[64:79]
	ds_read_b128 v[232:235], v172 offset:24832
	v_add_f32_e32 v182, v182, v82
	s_waitcnt lgkmcnt(9)
	v_mfma_f32_32x32x16_bf16 v[64:79], v[236:239], v[104:107], v[64:79]
	ds_read_b128 v[236:239], v169 offset:36864
	v_add_f32_e32 v182, v182, v83
	s_waitcnt lgkmcnt(9)
	v_mfma_f32_32x32x16_bf16 v[64:79], v[240:243], v[108:111], v[64:79]
	ds_read_b128 v[240:243], v170 offset:36864
	v_add_f32_e32 v182, v182, v84
	v_add_f32_e32 v182, v182, v85
	s_waitcnt lgkmcnt(9)
	v_mfma_f32_32x32x16_bf16 v[64:79], v[244:247], v[112:115], v[64:79]
	ds_read_b128 v[244:247], v171 offset:36864
	v_add_f32_e32 v182, v182, v86
	s_waitcnt lgkmcnt(9)
	v_mfma_f32_32x32x16_bf16 v[64:79], v[248:251], v[116:119], v[64:79]
	ds_read_b128 v[248:251], v172 offset:36864
	v_add_f32_e32 v182, v182, v87
	s_add_u32 s22, s65, 2
	s_cmp_ge_u32 s22, s50
	s_cbranch_scc1 .Lmla_skipdma_o
	s_add_u32 m0, s100, 0x0
	s_nop 0
	global_load_lds_dwordx4 v146, s[68:69]
	s_add_u32 m0, s101, 0x0
	s_nop 0
	global_load_lds_dwordx4 v148, s[70:71]
	s_add_u32 m0, s100, 0x2000
	s_nop 0
	global_load_lds_dwordx4 v150, s[68:69]
	s_add_u32 m0, s101, 0x2000
	s_nop 0
	global_load_lds_dwordx4 v152, s[70:71]
	s_add_u32 m0, s100, 0x4000
	s_nop 0
	global_load_lds_dwordx4 v154, s[68:69]
	s_add_u32 s68, s68, 0x18000
	s_addc_u32 s69, s69, 0
	s_add_u32 s70, s70, 0x10000
	s_addc_u32 s71, s71, 0
; #define SBAR() __builtin_amdgcn_sched_barrier(0)
; #define SGB(mask, n) __builtin_amdgcn_sched_group_barrier(mask, n, 0)
; #define BLOAD(b, k0) do { _Pragma("unroll") for (int i = 0; i < 3; ++i) glds16(Kh + (long)(k0) * 768 + bkoff[i], K_lds + (b) * 24576 + ldst[i]); \
;     _Pragma("unroll") for (int i = 0; i < 2; ++i) glds16(Vh + (long)(k0) * 512 + bvoff[i], V_lds + (b) * 16384 + ldst[i]); } while (0)
; DEV void attn_b_item(const Params& P, int layer, int batch, int item, char* lds) {
;     ...
;       for (int ks = 0; ks < 12; ++ks) kf[ks] = *reinterpret_cast<const bf16x8*>(Ks + kq + (((ks * 2 + hi) ^ ksw) << 4));
; #pragma unroll
;       for (int ks = 0; ks < 12; ++ks) p0 = __builtin_amdgcn_mfma_f32_32x32x16_bf16(kf[ks], qr[ks], p0, 0, 0, 0);
;       SGB(0x100, 4); SGB(0x008, 2); SGB(0x100, 2); SGB(0x008, 2); SGB(0x100, 2); SGB(0x008, 2); SGB(0x100, 2); SGB(0x008, 2); SGB(0x100, 2); SGB(0x008, 4);
;     }
;     SBAR();
;     if (j + 1 < NT) BLOAD((j + 1) & 1, (j + 1) * 64);
;     SBAR();
;     {
;       trq<0, 0>(vb, fa);
;       bf16x8 kf[12];
; #pragma unroll
;       for (int ks = 0; ks < 12; ++ks) kf[ks] = *reinterpret_cast<const bf16x8*>(Ks + kq + 32 * 384 + (((ks * 2 + hi) ^ ksw) << 4));
; #pragma unroll
;       for (int ks = 0; ks < 12; ++ks) p1 = __builtin_amdgcn_mfma_f32_32x32x16_bf16(kf[ks], qr[ks], p1, 0, 0, 0);
;       sm_exp(p0, lsum); sm_pack(p0, pa0, pa1);
;     }
;     asm volatile("s_waitcnt lgkmcnt(0)" ::: "memory"); SBAR();
;     trq<0, 2>(vb, fb);
;     mmaq(o[0], o[1], fa, pa0, pa1);
;     sm_exp(p1, lsum);
;     asm volatile("s_waitcnt lgkmcnt(0)" ::: "memory"); SBAR();
;     trq<2, 0>(vb, fa);
;     mmaq(o[2], o[3], fb, pa0, pa1);
;     sm_pack(p1, pa2, pa3);
;     asm volatile("s_waitcnt lgkmcnt(0)" ::: "memory"); SBAR();
;     trq<2, 2>(vb, fb);
;     mmaq(o[0], o[1], fa, pa2, pa3);
;     asm volatile("s_waitcnt lgkmcnt(0)" ::: "memory"); SBAR();
;     mmaq(o[2], o[3], fb, pa2, pa3);
;     asm volatile("s_waitcnt vmcnt(0)" ::: "memory");
;     __syncthreads();
.Lmla_skipdma_o:
	s_waitcnt lgkmcnt(9)
	v_mfma_f32_32x32x16_bf16 v[64:79], v[202:205], v[120:123], v[64:79]
	ds_read_b128 v[202:205], v169 offset:36992
	v_add_f32_e32 v182, v182, v88
	v_add_f32_e32 v182, v182, v89
	s_waitcnt lgkmcnt(9)
	v_mfma_f32_32x32x16_bf16 v[64:79], v[206:209], v[124:127], v[64:79]
	ds_read_b128 v[206:209], v170 offset:36992
	v_add_f32_e32 v182, v182, v90
	s_waitcnt lgkmcnt(9)
	v_mfma_f32_32x32x16_bf16 v[64:79], v[210:213], v[128:131], v[64:79]
	ds_read_b128 v[210:213], v171 offset:36992
	v_add_f32_e32 v182, v182, v91
	s_waitcnt lgkmcnt(9)
	v_mfma_f32_32x32x16_bf16 v[64:79], v[214:217], v[132:135], v[64:79]
	ds_read_b128 v[214:217], v172 offset:36992
	v_add_f32_e32 v182, v182, v92
	v_add_f32_e32 v182, v182, v93
	s_waitcnt lgkmcnt(9)
	v_mfma_f32_32x32x16_bf16 v[64:79], v[218:221], v[136:139], v[64:79]
	ds_read_b128 v[218:221], v169 offset:37120
	v_add_f32_e32 v182, v182, v94
	s_waitcnt lgkmcnt(9)
	v_mfma_f32_32x32x16_bf16 v[64:79], v[232:235], v[140:143], v[64:79]
	ds_read_b128 v[232:235], v170 offset:37120
	v_add_f32_e32 v182, v182, v95
	s_waitcnt lgkmcnt(9)
	v_mfma_f32_32x32x16_bf16 v[80:95], v[236:239], v[96:99], 0
	ds_read_b128 v[236:239], v171 offset:37120
	s_waitcnt lgkmcnt(9)
	v_mfma_f32_32x32x16_bf16 v[80:95], v[240:243], v[100:103], v[80:95]
	ds_read_b128 v[240:243], v172 offset:37120
	s_waitcnt lgkmcnt(9)
	v_mfma_f32_32x32x16_bf16 v[80:95], v[244:247], v[104:107], v[80:95]
	ds_read_b64_tr_b16 v[244:245], v166 offset:16384
	ds_read_b64_tr_b16 v[246:247], v166 offset:18432
	s_waitcnt lgkmcnt(10)
	v_mfma_f32_32x32x16_bf16 v[80:95], v[248:251], v[108:111], v[80:95]
	ds_read_b64_tr_b16 v[248:249], v166 offset:16896
	ds_read_b64_tr_b16 v[250:251], v166 offset:18944
	v_exp_f32_e32 v64, v64
	v_exp_f32_e32 v65, v65
	s_waitcnt lgkmcnt(11)
	v_mfma_f32_32x32x16_bf16 v[80:95], v[202:205], v[112:115], v[80:95]
	ds_read_b64_tr_b16 v[202:203], v166 offset:17408
	ds_read_b64_tr_b16 v[204:205], v166 offset:19456
	v_exp_f32_e32 v66, v66
	v_exp_f32_e32 v67, v67
	s_waitcnt lgkmcnt(12)
	v_mfma_f32_32x32x16_bf16 v[80:95], v[206:209], v[116:119], v[80:95]
	ds_read_b64_tr_b16 v[206:207], v166 offset:17920
	ds_read_b64_tr_b16 v[208:209], v166 offset:19968
	v_exp_f32_e32 v68, v68
	v_exp_f32_e32 v69, v69
	s_waitcnt lgkmcnt(13)
	v_mfma_f32_32x32x16_bf16 v[80:95], v[210:213], v[120:123], v[80:95]
	ds_read_b64_tr_b16 v[210:211], v166 offset:20480
	ds_read_b64_tr_b16 v[212:213], v166 offset:22528
	v_exp_f32_e32 v70, v70
	v_exp_f32_e32 v71, v71
	s_waitcnt lgkmcnt(14)
	v_mfma_f32_32x32x16_bf16 v[80:95], v[214:217], v[124:127], v[80:95]
	ds_read_b64_tr_b16 v[214:215], v166 offset:20992
	ds_read_b64_tr_b16 v[216:217], v166 offset:23040
	v_cvt_pk_bf16_f32 v174, v64, v65
	v_exp_f32_e32 v72, v72
	v_exp_f32_e32 v73, v73
	s_waitcnt lgkmcnt(14)
	v_mfma_f32_32x32x16_bf16 v[80:95], v[218:221], v[128:131], v[80:95]
	ds_read_b64_tr_b16 v[218:219], v166 offset:21504
	ds_read_b64_tr_b16 v[220:221], v166 offset:23552
	v_cvt_pk_bf16_f32 v175, v66, v67
	v_exp_f32_e32 v74, v74
	v_exp_f32_e32 v75, v75
	s_waitcnt lgkmcnt(14)
	v_mfma_f32_32x32x16_bf16 v[80:95], v[232:235], v[132:135], v[80:95]
	ds_read_b64_tr_b16 v[232:233], v166 offset:22016
	ds_read_b64_tr_b16 v[234:235], v166 offset:24064
	v_cvt_pk_bf16_f32 v176, v68, v69
	v_exp_f32_e32 v76, v76
	v_exp_f32_e32 v77, v77
	s_waitcnt lgkmcnt(14)
	v_mfma_f32_32x32x16_bf16 v[80:95], v[236:239], v[136:139], v[80:95]
	ds_read_b64_tr_b16 v[236:237], v166 offset:24576
	ds_read_b64_tr_b16 v[238:239], v166 offset:26624
	v_cvt_pk_bf16_f32 v177, v70, v71
	v_exp_f32_e32 v78, v78
	v_exp_f32_e32 v79, v79
	s_waitcnt lgkmcnt(14)
	v_mfma_f32_32x32x16_bf16 v[80:95], v[240:243], v[140:143], v[80:95]
	ds_read_b64_tr_b16 v[240:241], v166 offset:25088
	ds_read_b64_tr_b16 v[242:243], v166 offset:27136
	v_cvt_pk_bf16_f32 v178, v72, v73
	v_cvt_pk_bf16_f32 v179, v74, v75
	v_cvt_pk_bf16_f32 v180, v76, v77
	v_cvt_pk_bf16_f32 v181, v78, v79
	s_waitcnt lgkmcnt(14)
	v_mfma_f32_32x32x16_bf16 v[48:63], v[174:177], v[244:247], v[48:63]
	ds_read_b64_tr_b16 v[244:245], v166 offset:25600
	ds_read_b64_tr_b16 v[246:247], v166 offset:27648
	v_add_f32_e32 v182, v182, v64
	v_add_f32_e32 v182, v182, v65
	v_add_f32_e32 v182, v182, v66
	v_add_f32_e32 v182, v182, v67
	s_waitcnt lgkmcnt(14)
	v_mfma_f32_32x32x16_bf16 v[32:47], v[174:177], v[248:251], v[32:47]
	ds_read_b64_tr_b16 v[248:249], v166 offset:26112
	ds_read_b64_tr_b16 v[250:251], v166 offset:28160
	v_add_f32_e32 v182, v182, v68
	v_add_f32_e32 v182, v182, v69
	v_add_f32_e32 v182, v182, v70
	v_add_f32_e32 v182, v182, v71
	s_waitcnt lgkmcnt(14)
	v_mfma_f32_32x32x16_bf16 v[16:31], v[174:177], v[202:205], v[16:31]
	ds_read_b64_tr_b16 v[202:203], v166 offset:28672
	ds_read_b64_tr_b16 v[204:205], v166 offset:30720
	v_add_f32_e32 v182, v182, v72
	v_add_f32_e32 v182, v182, v73
	v_add_f32_e32 v182, v182, v74
	v_add_f32_e32 v182, v182, v75
	s_waitcnt lgkmcnt(14)
	v_mfma_f32_32x32x16_bf16 v[0:15], v[174:177], v[206:209], v[0:15]
	ds_read_b64_tr_b16 v[206:207], v166 offset:29184
	ds_read_b64_tr_b16 v[208:209], v166 offset:31232
	v_exp_f32_e32 v80, v80
	v_exp_f32_e32 v81, v81
	v_exp_f32_e32 v82, v82
	s_waitcnt lgkmcnt(14)
	v_mfma_f32_32x32x16_bf16 v[48:63], v[178:181], v[210:213], v[48:63]
	ds_read_b64_tr_b16 v[210:211], v166 offset:29696
	ds_read_b64_tr_b16 v[212:213], v166 offset:31744
	v_exp_f32_e32 v83, v83
	v_exp_f32_e32 v84, v84
	v_exp_f32_e32 v85, v85
	s_waitcnt lgkmcnt(14)
	v_mfma_f32_32x32x16_bf16 v[32:47], v[178:181], v[214:217], v[32:47]
	ds_read_b64_tr_b16 v[214:215], v166 offset:30208
	ds_read_b64_tr_b16 v[216:217], v166 offset:32256
	v_exp_f32_e32 v86, v86
	v_exp_f32_e32 v87, v87
	v_exp_f32_e32 v88, v88
	s_waitcnt lgkmcnt(14)
	v_mfma_f32_32x32x16_bf16 v[16:31], v[178:181], v[218:221], v[16:31]
	v_cvt_pk_bf16_f32 v194, v80, v81
	v_cvt_pk_bf16_f32 v195, v82, v83
	v_exp_f32_e32 v89, v89
	v_exp_f32_e32 v90, v90
	v_exp_f32_e32 v91, v91
	s_waitcnt lgkmcnt(14)
	v_mfma_f32_32x32x16_bf16 v[0:15], v[178:181], v[232:235], v[0:15]
	v_cvt_pk_bf16_f32 v196, v84, v85
	v_cvt_pk_bf16_f32 v197, v86, v87
	v_exp_f32_e32 v92, v92
	v_exp_f32_e32 v93, v93
	s_waitcnt lgkmcnt(14)
	v_mfma_f32_32x32x16_bf16 v[48:63], v[194:197], v[236:239], v[48:63]
	v_exp_f32_e32 v94, v94
	v_exp_f32_e32 v95, v95
	s_waitcnt lgkmcnt(12)
	v_mfma_f32_32x32x16_bf16 v[32:47], v[194:197], v[240:243], v[32:47]
	v_cvt_pk_bf16_f32 v198, v88, v89
	v_cvt_pk_bf16_f32 v199, v90, v91
	v_add_f32_e32 v182, v182, v76
	v_add_f32_e32 v182, v182, v77
	s_waitcnt lgkmcnt(10)
	v_mfma_f32_32x32x16_bf16 v[16:31], v[194:197], v[244:247], v[16:31]
	v_cvt_pk_bf16_f32 v200, v92, v93
	v_cvt_pk_bf16_f32 v201, v94, v95
	v_add_f32_e32 v182, v182, v78
	v_add_f32_e32 v182, v182, v79
	s_waitcnt lgkmcnt(8)
	v_mfma_f32_32x32x16_bf16 v[0:15], v[194:197], v[248:251], v[0:15]
	s_waitcnt lgkmcnt(0)
	s_waitcnt vmcnt(0)
	s_barrier
; #define SBAR() __builtin_amdgcn_sched_barrier(0)
; DEV void sm_exp(f32x16& p, float& lsum) {
; #pragma unroll
;   for (int r = 0; r < 16; ++r) p[r] = __builtin_amdgcn_exp2f(p[r]);
; #pragma unroll
;   for (int r = 0; r < 16; ++r) lsum += p[r];
; }
; DEV void attn_b_item(const Params& P, int layer, int batch, int item, char* lds) {
;     ...
;     trq<2, 2>(vb, fb);
;     mmaq(o[0], o[1], fa, pa2, pa3);
;     asm volatile("s_waitcnt lgkmcnt(0)" ::: "memory"); SBAR();
;     mmaq(o[2], o[3], fb, pa2, pa3);
	s_add_u32 s65, s65, 2
	s_cmp_lt_u32 s65, s50
	s_cbranch_scc1 .Lmla_loop
	v_mfma_f32_32x32x16_bf16 v[48:63], v[198:201], v[202:205], v[48:63]
	v_add_f32_e32 v182, v182, v80
	v_add_f32_e32 v182, v182, v81
	v_add_f32_e32 v182, v182, v82
	v_add_f32_e32 v182, v182, v83
	v_mfma_f32_32x32x16_bf16 v[32:47], v[198:201], v[206:209], v[32:47]
	v_add_f32_e32 v182, v182, v84
	v_add_f32_e32 v182, v182, v85
	v_add_f32_e32 v182, v182, v86
	v_add_f32_e32 v182, v182, v87
	v_mfma_f32_32x32x16_bf16 v[16:31], v[198:201], v[210:213], v[16:31]
	v_add_f32_e32 v182, v182, v88
	v_add_f32_e32 v182, v182, v89
	v_add_f32_e32 v182, v182, v90
	v_add_f32_e32 v182, v182, v91
	v_mfma_f32_32x32x16_bf16 v[0:15], v[198:201], v[214:217], v[0:15]
	v_add_f32_e32 v182, v182, v92
	v_add_f32_e32 v182, v182, v93
	v_add_f32_e32 v182, v182, v94
	v_add_f32_e32 v182, v182, v95
